# anorm row pass: 16-lane group sum via DPP moves (quad_perm, row_half_mirror, row_mirror) instead of four ds_bpermute round trips per row
# speedup vs baseline: 1.0058x; 1.0038x over previous
; DEVI unsigned pk_bf16(float lo, float hi) { unsigned r; asm("v_cvt_pk_bf16_f32 %0, %1, %2" : "=v"(r) : "v"(lo), "v"(hi)); return r; }
; DEVI float bf_lo(unsigned u) { return __uint_as_float(u << 16); }
; DEVI float bf_hi(unsigned u) { return __uint_as_float(u & 0xffff0000u); }
; DEVI float sigmoidf_(float x) { return __builtin_amdgcn_rcpf(1.0f + __builtin_amdgcn_exp2f(-x * LOG2E)); }
; __device__ __forceinline__ void anorm_phase(const Params& p) {
;     ...
;   for (int r = wave; r < M; r += nw) {
;     bf16_t* zr = Z + (size_t)r * LDZE;
;     const uint4 h0 = *(const uint4*)(zr + 1024 + 16 * lane), h1 = *(const uint4*)(zr + 1024 + 16 * lane + 8);
;     const uint4 o0 = *(const uint4*)(zr + 3072 + 16 * lane), o1 = *(const uint4*)(zr + 3072 + 16 * lane + 8);
;     const unsigned hu[8] = {h0.x, h0.y, h0.z, h0.w, h1.x, h1.y, h1.z, h1.w}, ou[8] = {o0.x, o0.y, o0.z, o0.w, o1.x, o1.y, o1.z, o1.w};
;     float hv[16], ov[16]; float ss = 0.f;
; #pragma unroll
;     for (int i = 0; i < 8; ++i) { hv[2 * i] = bf_lo(hu[i]); hv[2 * i + 1] = bf_hi(hu[i]); ov[2 * i] = bf_lo(ou[i]); ov[2 * i + 1] = bf_hi(ou[i]); ss += hv[2 * i] * hv[2 * i] + hv[2 * i + 1] * hv[2 * i + 1]; }
;     ss += __shfl_xor(ss, 1); ss += __shfl_xor(ss, 2); ss += __shfl_xor(ss, 4); ss += __shfl_xor(ss, 8);
;     const float rs = rsqrtf(ss * (1.0f / 256.0f) + EPS);
;     const float* gp = p.ev_a_norm + ((16 * lane) & 255);
;     unsigned res[8];
; #pragma unroll
;     for (int i = 0; i < 8; ++i) res[i] = pk_bf16(hv[2 * i] * rs * gp[2 * i] * sigmoidf_(ov[2 * i]), hv[2 * i + 1] * rs * gp[2 * i + 1] * sigmoidf_(ov[2 * i + 1]));
;     *(uint4*)(zr + 3072 + 16 * lane) = make_uint4(res[0], res[1], res[2], res[3]);
;     *(uint4*)(zr + 3072 + 16 * lane + 8) = make_uint4(res[4], res[5], res[6], res[7]);
;   }
.LBB0_790:
	global_load_dwordx4 v[24:27], v[14:15], off
	global_load_dwordx4 v[8:11], v[14:15], off offset:16
	v_add_co_u32_e32 v16, vcc, 0x1000, v14
	v_lshl_add_u64 v[40:41], v[14:15], 0, s[6:7]
	s_nop 0
	v_addc_co_u32_e32 v17, vcc, 0, v15, vcc
	global_load_dwordx4 v[0:3], v[12:13], off
	global_load_dwordx4 v[4:7], v[12:13], off offset:16
	global_load_dwordx4 v[28:31], v[12:13], off offset:32
	global_load_dwordx4 v[32:35], v[12:13], off offset:48
	global_load_dwordx4 v[36:39], v[16:17], off
	s_nop 0
	global_load_dwordx4 v[40:43], v[40:41], off offset:16
	v_add_u32_e32 v18, s20, v18
	v_cmp_lt_i32_e32 vcc, s9, v18
	s_or_b64 s[4:5], vcc, s[4:5]
	v_lshl_add_u64 v[14:15], v[14:15], 0, s[2:3]
	s_waitcnt vmcnt(7)
	v_lshlrev_b32_e32 v54, 16, v24
	v_lshlrev_b32_e32 v56, 16, v25
	v_and_b32_e32 v55, 0xffff0000, v24
	v_and_b32_e32 v57, 0xffff0000, v25
	v_lshlrev_b32_e32 v25, 16, v27
	v_lshlrev_b32_e32 v24, 16, v26
	s_waitcnt vmcnt(6)
	v_lshlrev_b32_e32 v47, 16, v11
	v_lshlrev_b32_e32 v46, 16, v10
	v_mul_f32_e32 v58, v54, v54
	v_mul_f32_e32 v59, v56, v56
	v_and_b32_e32 v27, 0xffff0000, v27
	v_and_b32_e32 v26, 0xffff0000, v26
	v_and_b32_e32 v11, 0xffff0000, v11
	v_and_b32_e32 v10, 0xffff0000, v10
	v_pk_mul_f32 v[48:49], v[24:25], v[24:25]
	v_pk_mul_f32 v[52:53], v[46:47], v[46:47]
	v_fmac_f32_e32 v58, v55, v55
	v_fmac_f32_e32 v59, v57, v57
	v_lshlrev_b32_e32 v45, 16, v9
	v_lshlrev_b32_e32 v44, 16, v8
	s_waitcnt vmcnt(1)
	v_lshlrev_b32_e32 v60, 16, v36
	v_and_b32_e32 v61, 0xffff0000, v36
	v_lshlrev_b32_e32 v62, 16, v37
	v_and_b32_e32 v63, 0xffff0000, v37
	v_lshlrev_b32_e32 v64, 16, v38
	v_and_b32_e32 v65, 0xffff0000, v38
	v_lshlrev_b32_e32 v66, 16, v39
	v_and_b32_e32 v67, 0xffff0000, v39
	v_pk_fma_f32 v[36:37], v[26:27], v[26:27], v[48:49]
	s_waitcnt vmcnt(0)
	v_lshlrev_b32_e32 v48, 16, v40
	v_and_b32_e32 v49, 0xffff0000, v40
	v_lshlrev_b32_e32 v68, 16, v41
	v_and_b32_e32 v69, 0xffff0000, v41
	v_pk_fma_f32 v[40:41], v[10:11], v[10:11], v[52:53]
	v_add_f32_e32 v52, v58, v59
	v_and_b32_e32 v9, 0xffff0000, v9
	v_and_b32_e32 v8, 0xffff0000, v8
	v_pk_mul_f32 v[50:51], v[44:45], v[44:45]
	v_mul_f32_e32 v53, 0xbfb8aa3b, v60
	v_mul_f32_e32 v58, 0xbfb8aa3b, v61
	v_mul_f32_e32 v59, 0xbfb8aa3b, v62
	v_mul_f32_e32 v60, 0xbfb8aa3b, v63
	v_mul_f32_e32 v61, 0xbfb8aa3b, v64
	v_mul_f32_e32 v62, 0xbfb8aa3b, v65
	v_mul_f32_e32 v63, 0xbfb8aa3b, v66
	v_mul_f32_e32 v64, 0xbfb8aa3b, v67
	v_mul_f32_e32 v65, 0xbfb8aa3b, v68
	v_mul_f32_e32 v66, 0xbfb8aa3b, v69
	v_add_f32_e32 v36, v52, v36
	v_pk_fma_f32 v[38:39], v[8:9], v[8:9], v[50:51]
	v_exp_f32_e32 v52, v53
	v_exp_f32_e32 v53, v58
	v_exp_f32_e32 v58, v59
	v_exp_f32_e32 v59, v60
	v_exp_f32_e32 v60, v61
	v_exp_f32_e32 v61, v62
	v_exp_f32_e32 v62, v63
	v_exp_f32_e32 v63, v64
	v_exp_f32_e32 v64, v65
	v_exp_f32_e32 v65, v66
	v_add_f32_e32 v36, v36, v37
	v_add_f32_e32 v36, v36, v38
	v_add_f32_e32 v36, v36, v39
	v_add_f32_e32 v36, v36, v40
	v_add_f32_e32 v37, 1.0, v52
	v_add_f32_e32 v38, 1.0, v53
	v_add_f32_e32 v39, 1.0, v58
	v_add_f32_e32 v40, 1.0, v59
	v_add_f32_e32 v52, 1.0, v60
	v_add_f32_e32 v53, 1.0, v61
	v_add_f32_e32 v58, 1.0, v62
	v_add_f32_e32 v59, 1.0, v63
	v_add_f32_e32 v60, 1.0, v64
	v_add_f32_e32 v61, 1.0, v65
	v_add_f32_e32 v36, v36, v41
	v_rcp_f32_e32 v41, v52
	v_rcp_f32_e32 v52, v53
	v_rcp_f32_e32 v53, v58
	v_rcp_f32_e32 v58, v59
	v_rcp_f32_e32 v59, v60
	v_rcp_f32_e32 v60, v61
	s_nop 1
	v_mov_b32_dpp v61, v36 quad_perm:[1,0,3,2] row_mask:0xf bank_mask:0xf
	v_lshlrev_b32_e32 v50, 16, v42
	v_and_b32_e32 v42, 0xffff0000, v42
	v_lshlrev_b32_e32 v51, 16, v43
	v_and_b32_e32 v43, 0xffff0000, v43
	s_waitcnt lgkmcnt(0)
	v_add_f32_e32 v36, v36, v61
	s_nop 1
	v_mov_b32_dpp v61, v36 quad_perm:[2,3,0,1] row_mask:0xf bank_mask:0xf
	v_mul_f32_e32 v48, 0xbfb8aa3b, v48
	v_mul_f32_e32 v49, 0xbfb8aa3b, v49
	v_mul_f32_e32 v50, 0xbfb8aa3b, v50
	v_mul_f32_e32 v42, 0xbfb8aa3b, v42
	s_waitcnt lgkmcnt(0)
	v_add_f32_e32 v36, v36, v61
	s_nop 1
	v_mov_b32_dpp v61, v36 row_half_mirror row_mask:0xf bank_mask:0xf
	v_mul_f32_e32 v51, 0xbfb8aa3b, v51
	v_mul_f32_e32 v43, 0xbfb8aa3b, v43
	v_exp_f32_e32 v48, v48
	v_exp_f32_e32 v49, v49
	s_waitcnt lgkmcnt(0)
	v_add_f32_e32 v36, v36, v61
	s_nop 1
	v_mov_b32_dpp v61, v36 row_mirror row_mask:0xf bank_mask:0xf
	v_exp_f32_e32 v50, v50
	v_exp_f32_e32 v42, v42
	v_exp_f32_e32 v51, v51
	v_exp_f32_e32 v43, v43
	s_waitcnt lgkmcnt(0)
	v_add_f32_e32 v36, v36, v61
	v_fmamk_f32 v36, v36, 0x3b800000, v23
	v_mul_f32_e32 v61, 0x4b800000, v36
	v_cmp_gt_f32_e32 vcc, s8, v36
	v_rcp_f32_e32 v37, v37
	v_rcp_f32_e32 v38, v38
	v_cndmask_b32_e32 v36, v36, v61, vcc
	v_rsq_f32_e32 v36, v36
	v_rcp_f32_e32 v39, v39
	v_rcp_f32_e32 v40, v40
	v_add_f32_e32 v48, 1.0, v48
	v_mul_f32_e32 v61, 0x45800000, v36
	v_add_f32_e32 v49, 1.0, v49
	v_add_f32_e32 v50, 1.0, v50
	v_add_f32_e32 v42, 1.0, v42
	v_add_f32_e32 v51, 1.0, v51
	v_add_f32_e32 v43, 1.0, v43
	v_cndmask_b32_e32 v36, v36, v61, vcc
	v_rcp_f32_e32 v48, v48
	v_rcp_f32_e32 v49, v49
	v_rcp_f32_e32 v50, v50
	v_rcp_f32_e32 v42, v42
	v_rcp_f32_e32 v51, v51
	v_rcp_f32_e32 v43, v43
	v_mul_f32_e32 v54, v36, v54
	v_mul_f32_e32 v55, v36, v55
	v_mul_f32_e32 v56, v36, v56
	v_mul_f32_e32 v57, v36, v57
	v_mul_f32_e32 v24, v36, v24
	v_mul_f32_e32 v26, v36, v26
	v_mul_f32_e32 v25, v36, v25
	v_mul_f32_e32 v27, v36, v27
	v_mul_f32_e32 v0, v0, v54
	v_mul_f32_e32 v1, v1, v55
	v_mul_f32_e32 v2, v2, v56
	v_mul_f32_e32 v3, v3, v57
	v_mul_f32_e32 v44, v36, v44
	v_mul_f32_e32 v8, v36, v8
	v_mul_f32_e32 v45, v36, v45
	v_mul_f32_e32 v9, v36, v9
	v_mul_f32_e32 v46, v36, v46
	v_mul_f32_e32 v10, v36, v10
	v_mul_f32_e32 v47, v36, v47
	v_mul_f32_e32 v11, v36, v11
	v_mul_f32_e32 v4, v4, v24
	v_mul_f32_e32 v5, v5, v26
	v_mul_f32_e32 v6, v25, v6
	v_mul_f32_e32 v7, v27, v7
	v_mul_f32_e32 v0, v37, v0
	v_mul_f32_e32 v1, v38, v1
	v_mul_f32_e32 v2, v39, v2
	v_mul_f32_e32 v3, v40, v3
	v_mul_f32_e32 v24, v44, v28
	v_mul_f32_e32 v8, v8, v29
	v_mul_f32_e32 v25, v45, v30
	v_mul_f32_e32 v9, v9, v31
	v_mul_f32_e32 v26, v46, v32
	v_mul_f32_e32 v10, v10, v33
	v_mul_f32_e32 v27, v47, v34
	v_mul_f32_e32 v11, v11, v35
	v_mul_f32_e32 v4, v41, v4
	v_mul_f32_e32 v5, v52, v5
	v_mul_f32_e32 v6, v53, v6
	v_mul_f32_e32 v7, v58, v7
	v_cvt_pk_bf16_f32 v0, v0, v1
	v_cvt_pk_bf16_f32 v1, v2, v3
	v_cvt_pk_bf16_f32 v2, v4, v5
	v_cvt_pk_bf16_f32 v3, v6, v7
	v_mul_f32_e32 v24, v48, v24
	v_mul_f32_e32 v8, v49, v8
	v_mul_f32_e32 v25, v59, v25
	v_mul_f32_e32 v9, v60, v9
	v_mul_f32_e32 v26, v50, v26
	v_mul_f32_e32 v10, v42, v10
	v_mul_f32_e32 v27, v51, v27
	v_mul_f32_e32 v11, v43, v11
	v_cvt_pk_bf16_f32 v4, v24, v8
	v_cvt_pk_bf16_f32 v5, v25, v9
	v_cvt_pk_bf16_f32 v6, v26, v10
	v_cvt_pk_bf16_f32 v7, v27, v11
	global_store_dwordx4 v[16:17], v[0:3], off
	global_store_dwordx4 v[16:17], v[4:7], off offset:16
	s_andn2_b64 exec, exec, s[4:5]
	s_cbranch_execnz .LBB0_790
